# v60 + role-asymmetric wave priority in HGRN scan: compute waves s_setprio 2, staging waves 0
# speedup vs baseline: 1.0036x; 1.0036x over previous
; DI void hgrn_scan_mfma(const Params& p, char* shm) {
;     ...
;     for (int u = bx; u < 128; u += gridDim.x) {
;         const int dir = u & 1, head = (u >> 1) & 7, b = u >> 4;
;         const unsigned char* Fb = P + (dir ? P_HF1 : P_HF0); bf16_t* Oo = dir ? (bf16_t*)(p.ws + WS_P + P_HOB) : (bf16_t*)(p.ws + WS_H);
;         f32x4 S[8];
; #pragma unroll
;         for (int kt = 0; kt < 8; ++kt) S[kt] = (f32x4){0.f, 0.f, 0.f, 0.f};
;         const int lt = tid >> 4, lp = tid & 15;
;         u32x4 ra0, ra1, ra2, ra3, ra4, rb0, rb1, rb2, rb3, rb4;
;     ...
;         HG_LOAD(0, ra0, ra1, ra2, ra3, ra4); HG_LOAD(1, rb0, rb1, rb2, rb3, rb4);
;         for (int ch2 = 0; ch2 < LT / C; ch2 += 2) {
; #pragma unroll
;           for (int hh = 0; hh < 2; ++hh) {
;             const int ch = ch2 + hh;
;             if (hh == 0) HG_STAGE(ch, ra0, ra1, ra2, ra3, ra4); else HG_STAGE(ch, rb0, rb1, rb2, rb3, rb4);
;             { const bf16_t* kt16 = (const bf16_t*)KtL; const bf16_t* v16 = (const bf16_t*)VL; const int vcol = w * 16 + l15;
;     ...
;               const bf16x8 vf = __builtin_bit_cast(bf16x8, (u32x4){HG_U2(v16, g * 4 + 0, g * 4 + 1, vcol), HG_U2(v16, g * 4 + 2, g * 4 + 3, vcol), HG_U2(v16, 16 + g * 4 + 0, 16 + g * 4 + 1, vcol), HG_U2(v16, 16 + g * 4 + 2, 16 + g * 4 + 3, vcol)});
;               f32x4 sc00 = (f32x4){0.f, 0.f, 0.f, 0.f}, sc01 = sc00, sc11 = sc00, o0 = sc00, o1 = sc00;
; #pragma unroll
;               for (int kc = 0; kc < 4; ++kc) {
;                   const bf16x8 aK0 = *(const bf16x8*)(KtL + l15 * QS + kc * 64 + g * 16), aK1 = *(const bf16x8*)(KtL + (16 + l15) * QS + kc * 64 + g * 16);
;                   const bf16x8 bQ0 = *(const bf16x8*)(QtL + l15 * QS + kc * 64 + g * 16), bQ1 = *(const bf16x8*)(QtL + (16 + l15) * QS + kc * 64 + g * 16);
.LBB0_2416:
	s_or_b64 exec, exec, s[14:15]
	v_cndmask_b32_e64 v3, 0, 1, s[40:41]
	v_lshl_add_u64 v[142:143], s[0:1], 0, v[0:1]
	v_readfirstlane_b32 s14, v3
	s_lshl_b32 s55, s14, 3
	s_lshl_b32 s14, s31, 2
	s_and_b32 s56, s14, 0xe00
	s_and_b64 s[14:15], s[12:13], exec
	s_cselect_b32 s14, s72, 0x146da000
	s_add_u32 s14, s68, s14
	s_addc_u32 s15, s69, 0
	s_add_u32 s14, s14, s38
	s_addc_u32 s15, s15, 0
	v_lshl_add_u64 v[132:133], v[120:121], 1, s[14:15]
	s_mov_b64 s[78:79], s[14:15]
	s_and_b64 s[14:15], s[12:13], exec
	s_cselect_b32 s15, 0, -1
	s_cselect_b32 s14, s73, 0xfffffc00
	s_add_i32 s0, s54, s55
	s_mul_hi_i32 s1, s0, 0x48000
	s_mul_i32 s0, s0, 0x48000
	s_or_b32 s0, s0, s56
	v_mov_b32_e32 v44, 0
	s_mov_b32 s74, 0
	v_lshl_add_u64 v[128:129], v[116:117], 0, s[38:39]
	v_lshl_add_u64 v[130:131], v[118:119], 0, s[38:39]
	v_mul_hi_i32_i24_e32 v135, s14, v147
	v_mul_i32_i24_e32 v134, s14, v147
	s_lshl_b64 s[52:53], s[14:15], 5
	v_mul_hi_i32_i24_e32 v137, s14, v152
	v_mul_i32_i24_e32 v136, s14, v152
	v_mul_hi_i32_i24_e32 v139, s14, v153
	v_mul_i32_i24_e32 v138, s14, v153
	v_mul_hi_i32_i24_e32 v141, s14, v154
	v_mul_i32_i24_e32 v140, s14, v154
	v_lshl_add_u64 v[144:145], v[122:123], 0, s[0:1]
	s_movk_i32 s38, 0xffe0
	s_mov_b32 s76, 0
	v_mov_b32_e32 v45, v44
	v_mov_b32_e32 v46, v44
	v_mov_b32_e32 v47, v44
	v_mov_b32_e32 v48, v44
	v_mov_b32_e32 v49, v44
	v_mov_b32_e32 v50, v44
	v_mov_b32_e32 v51, v44
	v_mov_b32_e32 v52, v44
	v_mov_b32_e32 v53, v44
	v_mov_b32_e32 v54, v44
	v_mov_b32_e32 v55, v44
	v_mov_b32_e32 v56, v44
	v_mov_b32_e32 v57, v44
	v_mov_b32_e32 v58, v44
	v_mov_b32_e32 v59, v44
	v_mov_b32_e32 v60, v44
	v_mov_b32_e32 v61, v44
	v_mov_b32_e32 v62, v44
	v_mov_b32_e32 v63, v44
	v_mov_b32_e32 v64, v44
	v_mov_b32_e32 v65, v44
	v_mov_b32_e32 v66, v44
	v_mov_b32_e32 v67, v44
	v_mov_b32_e32 v72, v44
	v_mov_b32_e32 v73, v44
	v_mov_b32_e32 v74, v44
	v_mov_b32_e32 v75, v44
	v_mov_b32_e32 v68, v44
	v_mov_b32_e32 v69, v44
	v_mov_b32_e32 v70, v44
	v_mov_b32_e32 v71, v44
	s_cmp_lg_u32 s100, 0
	s_cbranch_scc1 .Lscanh_pro
	v_add_u32_e32 v195, 0x8000, v161
	v_add_u32_e32 v197, 0x9000, v161
	v_bfe_u32 v200, v252, 4, 2
	v_bfe_u32 v201, v252, 2, 2
	v_lshl_add_u32 v200, v200, 2, v201
	v_mul_u32_u24_e32 v199, 0x110, v200
	v_and_b32_e32 v201, 3, v252
	v_lshl_add_u32 v199, v201, 3, v199
	v_and_b32_e32 v198, -16, v120
	v_lshl_add_u32 v198, v198, 1, v199
	v_bfe_u32 v200, v252, 4, 2
	v_mul_u32_u24_e32 v196, 576, v200
	v_and_b32_e32 v200, 15, v252
	v_lshl_add_u32 v196, v200, 1, v196
	v_lshrrev_b32_e32 v202, 6, v252
	v_lshl_add_u32 v196, v202, 5, v196
	v_add_u32_e32 v196, 0x1a200, v196
	s_setprio 2

; DI void hgrn_scan_mfma(const Params& p, char* shm) {
;     ...
;         for (int ch2 = 0; ch2 < LT / C; ch2 += 2) {
; #pragma unroll
;           for (int hh = 0; hh < 2; ++hh) {
;             const int ch = ch2 + hh;
;             if (hh == 0) HG_STAGE(ch, ra0, ra1, ra2, ra3, ra4); else HG_STAGE(ch, rb0, rb1, rb2, rb3, rb4);
;             { const bf16_t* kt16 = (const bf16_t*)KtL; const bf16_t* v16 = (const bf16_t*)VL; const int vcol = w * 16 + l15;
;     ...
;               const bf16x8 vf = __builtin_bit_cast(bf16x8, (u32x4){HG_U2(v16, g * 4 + 0, g * 4 + 1, vcol), HG_U2(v16, g * 4 + 2, g * 4 + 3, vcol), HG_U2(v16, 16 + g * 4 + 0, 16 + g * 4 + 1, vcol), HG_U2(v16, 16 + g * 4 + 2, 16 + g * 4 + 3, vcol)});
;               f32x4 sc00 = (f32x4){0.f, 0.f, 0.f, 0.f}, sc01 = sc00, sc11 = sc00, o0 = sc00, o1 = sc00;
; #pragma unroll
;               for (int kc = 0; kc < 4; ++kc) {
;                   const bf16x8 aK0 = *(const bf16x8*)(KtL + l15 * QS + kc * 64 + g * 16), aK1 = *(const bf16x8*)(KtL + (16 + l15) * QS + kc * 64 + g * 16);
;                   const bf16x8 bQ0 = *(const bf16x8*)(QtL + l15 * QS + kc * 64 + g * 16), bQ1 = *(const bf16x8*)(QtL + (16 + l15) * QS + kc * 64 + g * 16);
;                   sc00 = __builtin_amdgcn_mfma_f32_16x16x32_bf16(aK0, bQ0, sc00, 0, 0, 0);
;                   sc01 = __builtin_amdgcn_mfma_f32_16x16x32_bf16(aK0, bQ1, sc01, 0, 0, 0);
;                   sc11 = __builtin_amdgcn_mfma_f32_16x16x32_bf16(aK1, bQ1, sc11, 0, 0, 0);
;                   const int kp = kc;
;                   const u32x2 qa0 = *(const u32x2*)(QtL + l15 * QS + ((2 * kp) * 16 + g * 4) * 2), qb0 = *(const u32x2*)(QtL + l15 * QS + ((2 * kp + 1) * 16 + g * 4) * 2);
;                   const u32x2 qa1 = *(const u32x2*)(QtL + (16 + l15) * QS + ((2 * kp) * 16 + g * 4) * 2), qb1 = *(const u32x2*)(QtL + (16 + l15) * QS + ((2 * kp + 1) * 16 + g * 4) * 2);
;                   const bf16x8 sw = __builtin_bit_cast(bf16x8, (u32x4){pack2(S[2 * kp][0], S[2 * kp][1]), pack2(S[2 * kp][2], S[2 * kp][3]), pack2(S[2 * kp + 1][0], S[2 * kp + 1][1]), pack2(S[2 * kp + 1][2], S[2 * kp + 1][3])});
;                   o0 = __builtin_amdgcn_mfma_f32_16x16x32_bf16(__builtin_bit_cast(bf16x8, (u32x4){qa0.x, qa0.y, qb0.x, qb0.y}), sw, o0, 0, 0, 0);
;                   o1 = __builtin_amdgcn_mfma_f32_16x16x32_bf16(__builtin_bit_cast(bf16x8, (u32x4){qa1.x, qa1.y, qb1.x, qb1.y}), sw, o1, 0, 0, 0); }
.Lscanc_exit:
	s_waitcnt lgkmcnt(0)
	s_barrier
	s_setprio 0
	s_branch .LBB0_2411
